# MLA-up tile loop: counted vmcnt(32) for the prefetched weight tile instead of vmcnt(0) (stores of the previous tile stay in flight)
# speedup vs baseline: 1.0006x; 1.0006x over previous
; DI int crow(int r, int hh) { return (r & 3) + 8 * (r >> 2) + 4 * hh; }
; DI void phase_mla_up(const Params& p, int layer, char* lds) {
;     ...
;       const int NCT2 = (NCT + 1) / 2, NOUT = NCT * 64;
;       u32x4 rw[6];
;       auto wload = [&](int ct) {
;         int tl = tid; asm volatile("" : "+v"(tl));
; #pragma unroll
;         for (int i = 0; i < 6; ++i) { const int c = tl + NTHR * i; if (c < 128 * CPR) rw[i] = *(const u32x4*)(Wt + (size_t)ct * 128 * K + c * 8); }
;       };
;       __syncthreads();
;       float rv[16];
; #pragma unroll
;       for (int r = 0; r < 16; ++r) rv[r] = rinv[32 * wm + crow(r, hh)] * (part == 0 ? QSC : 1.f);
;       const int rowb = m0 + 32 * wm + 4 * hh;
;       const int bq = m0 >> 13, srow = rowb & (S - 1);
.LBB0_188:
	s_or_b64 exec, exec, s[26:27]
	v_cndmask_b32_e64 v4, 1.0, v217, s[12:13]
	s_waitcnt lgkmcnt(3)
	v_mul_f32_e32 v95, v4, v18
	v_mul_f32_e32 v96, v4, v19
	v_mul_f32_e32 v97, v4, v20
	v_mul_f32_e32 v98, v4, v21
	s_waitcnt lgkmcnt(2)
	v_mul_f32_e32 v99, v4, v14
	v_mul_f32_e32 v100, v4, v15
	v_mul_f32_e32 v101, v4, v16
	v_mul_f32_e32 v102, v4, v17
	s_waitcnt lgkmcnt(1)
	v_mul_f32_e32 v103, v4, v10
	v_mul_f32_e32 v104, v4, v11
	v_mul_f32_e32 v105, v4, v12
	v_mul_f32_e32 v106, v4, v13
	s_waitcnt lgkmcnt(0)
	v_mul_f32_e32 v107, v4, v6
	v_mul_f32_e32 v108, v4, v7
	v_mul_f32_e32 v109, v4, v8
	v_mul_f32_e32 v110, v4, v9
	v_mul_f32_e32 v4, 0x4f7ffffe, v22
	v_cvt_u32_f32_e32 v4, v4
	s_and_b64 s[26:27], s[12:13], exec
	s_cselect_b32 s26, 9, 12
	s_add_i32 s27, s26, 1
	s_sub_i32 s12, 0, s29
	s_lshr_b32 s77, s27, 1
	s_lshl_b32 s73, s26, 6
	v_mul_lo_u32 v6, s12, v4
	s_lshl_b32 s49, s49, 8
	v_mul_hi_u32 v6, v4, v6
	s_add_u32 s24, s24, s49
	s_mov_b32 s53, 0
	v_add_u32_e32 v111, v4, v6
	s_addc_u32 s25, s25, 0
	v_mov_b32_e32 v78, v89
	s_waitcnt vmcnt(0)
	s_branch .LBB0_191

; DI void phase_mla_up(const Params& p, int layer, char* lds) {
;     ...
;         {
;           int tl = tid; asm volatile("" : "+v"(tl));
; #pragma unroll
;           for (int i = 0; i < 6; ++i) { const int c = tl + NTHR * i, row = c / CPR, ch = c % CPR; if (c < 128 * CPR) *(u32x4*)(Bs + row * STR + ch * 16) = rw[i]; }
;         }
.LBB0_191:
	v_mov_b32_e32 v4, v59
	s_nop 0
	v_cmp_gt_i32_e32 vcc, s93, v4
	s_and_saveexec_b64 s[12:13], vcc
	s_cbranch_execz .LBB0_193
	v_sub_u32_e32 v7, 0, v4
	v_max_i32_e32 v7, v4, v7
	v_mul_hi_u32 v8, v7, v111
	v_mul_lo_u32 v9, v8, s29
	v_sub_u32_e32 v7, v7, v9
	v_add_u32_e32 v9, 1, v8
	v_cmp_le_u32_e32 vcc, s29, v7
	v_ashrrev_i32_e32 v6, 31, v4
	s_nop 0
	v_cndmask_b32_e32 v8, v8, v9, vcc
	v_subrev_u32_e32 v9, s29, v7
	v_cndmask_b32_e32 v7, v7, v9, vcc
	v_add_u32_e32 v9, 1, v8
	v_cmp_le_u32_e32 vcc, s29, v7
	s_nop 1
	v_cndmask_b32_e32 v7, v8, v9, vcc
	v_xor_b32_e32 v7, v7, v6
	v_sub_u32_e32 v6, v7, v6
	v_mul_lo_u32 v7, v6, s29
	v_sub_u32_e32 v7, v4, v7
	v_mul_lo_u32 v6, v6, s76
	v_lshlrev_b32_e32 v7, 4, v7
	v_add3_u32 v6, 0, v6, v7
	s_waitcnt vmcnt(32)
	ds_write_b128 v6, v[0:3] offset:51200
.LBB0_193:
	s_or_b64 exec, exec, s[12:13]
	v_add_u32_e32 v6, 0x200, v4
	v_cmp_gt_i32_e32 vcc, s93, v6
	s_and_saveexec_b64 s[12:13], vcc
	s_cbranch_execz .LBB0_195
	v_sub_u32_e32 v8, 0, v6
	v_max_i32_e32 v8, v6, v8
	v_mul_hi_u32 v9, v8, v111
	v_mul_lo_u32 v10, v9, s29
	v_sub_u32_e32 v8, v8, v10
	v_add_u32_e32 v10, 1, v9
	v_cmp_le_u32_e32 vcc, s29, v8
	v_ashrrev_i32_e32 v7, 31, v6
	s_nop 0
	v_cndmask_b32_e32 v9, v9, v10, vcc
	v_subrev_u32_e32 v10, s29, v8
	v_cndmask_b32_e32 v8, v8, v10, vcc
	v_add_u32_e32 v10, 1, v9
	v_cmp_le_u32_e32 vcc, s29, v8
	s_nop 1
	v_cndmask_b32_e32 v8, v9, v10, vcc
	v_xor_b32_e32 v8, v8, v7
	v_sub_u32_e32 v7, v8, v7
	v_mul_lo_u32 v8, v7, s29
	v_sub_u32_e32 v6, v6, v8
	v_mul_lo_u32 v7, v7, s76
	v_lshlrev_b32_e32 v6, 4, v6
	v_add3_u32 v6, 0, v7, v6
	s_waitcnt vmcnt(32)
	ds_write_b128 v6, v[38:41] offset:51200
.LBB0_195:
	s_or_b64 exec, exec, s[12:13]
	v_add_u32_e32 v6, 0x400, v4
	v_cmp_gt_i32_e32 vcc, s93, v6
	s_and_saveexec_b64 s[12:13], vcc
	s_cbranch_execz .LBB0_197
	v_sub_u32_e32 v8, 0, v6
	v_max_i32_e32 v8, v6, v8
	v_mul_hi_u32 v9, v8, v111
	v_mul_lo_u32 v10, v9, s29
	v_sub_u32_e32 v8, v8, v10
	v_add_u32_e32 v10, 1, v9
	v_cmp_le_u32_e32 vcc, s29, v8
	v_ashrrev_i32_e32 v7, 31, v6
	s_nop 0
	v_cndmask_b32_e32 v9, v9, v10, vcc
	v_subrev_u32_e32 v10, s29, v8
	v_cndmask_b32_e32 v8, v8, v10, vcc
	v_add_u32_e32 v10, 1, v9
	v_cmp_le_u32_e32 vcc, s29, v8
	s_nop 1
	v_cndmask_b32_e32 v8, v9, v10, vcc
	v_xor_b32_e32 v8, v8, v7
	v_sub_u32_e32 v7, v8, v7
	v_mul_lo_u32 v8, v7, s29
	v_sub_u32_e32 v6, v6, v8
	v_mul_lo_u32 v7, v7, s76
	v_lshlrev_b32_e32 v6, 4, v6
	v_add3_u32 v6, 0, v7, v6
	s_waitcnt vmcnt(32)
	ds_write_b128 v6, v[42:45] offset:51200
.LBB0_197:
	s_or_b64 exec, exec, s[12:13]
	v_add_u32_e32 v6, 0x600, v4
	v_cmp_gt_i32_e32 vcc, s93, v6
	s_and_saveexec_b64 s[12:13], vcc
	s_cbranch_execz .LBB0_199
	v_sub_u32_e32 v8, 0, v6
	v_max_i32_e32 v8, v6, v8
	v_mul_hi_u32 v9, v8, v111
	v_mul_lo_u32 v10, v9, s29
	v_sub_u32_e32 v8, v8, v10
	v_add_u32_e32 v10, 1, v9
	v_cmp_le_u32_e32 vcc, s29, v8
	v_ashrrev_i32_e32 v7, 31, v6
	s_nop 0
	v_cndmask_b32_e32 v9, v9, v10, vcc
	v_subrev_u32_e32 v10, s29, v8
	v_cndmask_b32_e32 v8, v8, v10, vcc
	v_add_u32_e32 v10, 1, v9
	v_cmp_le_u32_e32 vcc, s29, v8
	s_nop 1
	v_cndmask_b32_e32 v8, v9, v10, vcc
	v_xor_b32_e32 v8, v8, v7
	v_sub_u32_e32 v7, v8, v7
	v_mul_lo_u32 v8, v7, s29
	v_sub_u32_e32 v6, v6, v8
	v_mul_lo_u32 v7, v7, s76
	v_lshlrev_b32_e32 v6, 4, v6
	v_add3_u32 v6, 0, v7, v6
	s_waitcnt vmcnt(32)
	ds_write_b128 v6, v[46:49] offset:51200
.LBB0_199:
	s_or_b64 exec, exec, s[12:13]
	v_add_u32_e32 v6, 0x800, v4
	v_cmp_gt_i32_e32 vcc, s93, v6
	s_and_saveexec_b64 s[12:13], vcc
	s_cbranch_execz .LBB0_201
	v_sub_u32_e32 v8, 0, v6
	v_max_i32_e32 v8, v6, v8
	v_mul_hi_u32 v9, v8, v111
	v_mul_lo_u32 v10, v9, s29
	v_sub_u32_e32 v8, v8, v10
	v_add_u32_e32 v10, 1, v9
	v_cmp_le_u32_e32 vcc, s29, v8
	v_ashrrev_i32_e32 v7, 31, v6
	s_nop 0
	v_cndmask_b32_e32 v9, v9, v10, vcc
	v_subrev_u32_e32 v10, s29, v8
	v_cndmask_b32_e32 v8, v8, v10, vcc
	v_add_u32_e32 v10, 1, v9
	v_cmp_le_u32_e32 vcc, s29, v8
	s_nop 1
	v_cndmask_b32_e32 v8, v9, v10, vcc
	v_xor_b32_e32 v8, v8, v7
	v_sub_u32_e32 v7, v8, v7
	v_mul_lo_u32 v8, v7, s29
	v_sub_u32_e32 v6, v6, v8
	v_mul_lo_u32 v7, v7, s76
	v_lshlrev_b32_e32 v6, 4, v6
	v_add3_u32 v6, 0, v7, v6
	s_waitcnt vmcnt(32)
	ds_write_b128 v6, v[50:53] offset:51200
.LBB0_201:
	s_or_b64 exec, exec, s[12:13]
	v_add_u32_e32 v4, 0xa00, v4
	v_cmp_gt_i32_e32 vcc, s93, v4
	s_and_saveexec_b64 s[12:13], vcc
	s_cbranch_execz .LBB0_203
	v_sub_u32_e32 v7, 0, v4
	v_max_i32_e32 v7, v4, v7
	v_mul_hi_u32 v8, v7, v111
	v_mul_lo_u32 v9, v8, s29
	v_sub_u32_e32 v7, v7, v9
	v_add_u32_e32 v9, 1, v8
	v_cmp_le_u32_e32 vcc, s29, v7
	v_ashrrev_i32_e32 v6, 31, v4
	s_nop 0
	v_cndmask_b32_e32 v8, v8, v9, vcc
	v_subrev_u32_e32 v9, s29, v7
	v_cndmask_b32_e32 v7, v7, v9, vcc
	v_add_u32_e32 v9, 1, v8
	v_cmp_le_u32_e32 vcc, s29, v7
	s_nop 1
	v_cndmask_b32_e32 v7, v8, v9, vcc
	v_xor_b32_e32 v7, v7, v6
	v_sub_u32_e32 v6, v7, v6
	v_mul_lo_u32 v7, v6, s29
	v_sub_u32_e32 v4, v4, v7
	v_mul_lo_u32 v6, v6, s76
	v_lshlrev_b32_e32 v4, 4, v4
	v_add3_u32 v4, 0, v6, v4
	s_waitcnt vmcnt(32)
	ds_write_b128 v4, v[54:57] offset:51200
